# plus: first QK MFMA of the loop's first half-step issued ahead of the row-sum/pack VALU block
# baseline (speedup 1.0000x reference)
; #define TWAIT_BAR(N) asm volatile("s_waitcnt vmcnt(" #N ") lgkmcnt(0)\n\ts_barrier" ::: "memory")
; #define RESC() do { if constexpr (!NOMAX) if (resc) { asm volatile("s_waitcnt lgkmcnt(0)" ::: "memory"); \
;         _Pragma("unroll") for (int d_ = 0; d_ < 2; ++d_) _Pragma("unroll") for (int r = 0; r < 16; ++r) o[d_][r] *= wsf[crow(r, hi)]; } } while (0)
; #define ROT() do { sl_prev = sl_cur; sl_cur = sl_next; sl_next = (sl_next == 2 * SLOTB) ? 0 : sl_next + SLOTB; } while (0)
; #define RESC() do { if constexpr (!NOMAX) if (resc) { asm volatile("s_waitcnt lgkmcnt(0)" ::: "memory"); \
;         _Pragma("unroll") for (int d_ = 0; d_ < 4; ++d_) _Pragma("unroll") for (int r = 0; r < 16; ++r) o[d_][r] *= wsf[crow(r, hi)]; } } while (0)
; #define ROT() do { sl_prev = sl_cur; sl_cur = sl_next; sl_next = (sl_next == 2) ? 0 : sl_next + 1; } while (0)
; #define RESC() do { if (resc) { asm volatile("s_waitcnt lgkmcnt(0)" ::: "memory"); \
;         _Pragma("unroll") for (int d_ = 0; d_ < 4; ++d_) _Pragma("unroll") for (int r = 0; r < 16; ++r) o[d_][r] *= wsf[crow(r, hi)]; } } while (0)
; template <bool NOMAX>
; __device__ __forceinline__ void diff_unit(const AttnCtx& C, int u, LAS unsigned char* lds) {
;     ...
;     int kk = 1;
;     for (; kk + 7 < n; kk += 2) {
;         STEP(pB0, pB1, pA0, pA1, kk, true, true, true, false);     TWAIT_BAR(3); RESC(); ROT();
;         STEP(pA0, pA1, pB0, pB1, kk + 1, true, true, true, false); TWAIT_BAR(3); RESC(); ROT();
.LBB0_463:
	s_mov_b32 s8, s60
	s_mov_b32 s9, s16
	s_mov_b32 s10, s59
	ds_read_b128 v[4:7], v219 offset:1024
	v_lshl_add_u32 v207, s11, 14, v214
	s_waitcnt lgkmcnt(1)
	v_mfma_f32_32x32x16_bf16 v[132:147], v[192:195], v[116:119], 0
	v_add_f32_e32 v2, v100, v101
	v_add_f32_e32 v2, v102, v2
	v_add_f32_e32 v2, v103, v2
	v_add_f32_e32 v2, v104, v2
	v_add_f32_e32 v2, v105, v2
	v_cvt_pk_bf16_f32 v160, v100, v101
	v_cvt_pk_bf16_f32 v161, v102, v103
	v_mfma_f32_32x32x16_bf16 v[116:131], v[184:187], v[116:119], 0
	v_add_f32_e32 v2, v106, v2
	v_add_f32_e32 v2, v107, v2
	v_add_f32_e32 v2, v108, v2
	v_add_f32_e32 v2, v109, v2
	v_cvt_pk_bf16_f32 v162, v104, v105
	v_cvt_pk_bf16_f32 v163, v106, v107
	ds_read_b128 v[10:13], v219 offset:2048
	ds_read_b64_tr_b16 v[14:15], v207 offset:24576
	ds_read_b64_tr_b16 v[16:17], v207 offset:25088
	v_add_f32_e32 v2, v110, v2
	v_add_f32_e32 v2, v111, v2
	v_add_f32_e32 v2, v112, v2
	v_add_f32_e32 v2, v113, v2
	v_cvt_pk_bf16_f32 v156, v108, v109
	v_cvt_pk_bf16_f32 v157, v110, v111
	s_waitcnt lgkmcnt(3)
	v_mfma_f32_32x32x16_bf16 v[132:147], v[188:191], v[4:7], v[132:147]
	v_mfma_f32_32x32x16_bf16 v[116:131], v[180:183], v[4:7], v[116:131]
	v_add_f32_e32 v2, v114, v2
	v_add_f32_e32 v2, v115, v2
	v_add_f32_e32 v2, v84, v2
	v_add_f32_e32 v2, v85, v2
	v_cvt_pk_bf16_f32 v158, v112, v113
	v_cvt_pk_bf16_f32 v159, v114, v115
	ds_read_b128 v[4:7], v219 offset:3072
	ds_read_b64_tr_b16 v[100:101], v207 offset:28672
	ds_read_b64_tr_b16 v[102:103], v207 offset:29184
	v_add_f32_e32 v2, v86, v2
	v_add_f32_e32 v2, v87, v2
	v_add_f32_e32 v2, v88, v2
	v_add_f32_e32 v2, v89, v2
	v_cvt_pk_bf16_f32 v152, v84, v85
	v_cvt_pk_bf16_f32 v153, v86, v87
	s_waitcnt lgkmcnt(5)
	v_mfma_f32_32x32x16_bf16 v[132:147], v[176:179], v[10:13], v[132:147]
	v_mfma_f32_32x32x16_bf16 v[116:131], v[172:175], v[10:13], v[116:131]
	v_add_f32_e32 v2, v90, v2
	v_add_f32_e32 v2, v91, v2
	v_add_f32_e32 v2, v92, v2
	v_add_f32_e32 v2, v93, v2
	v_cvt_pk_bf16_f32 v154, v88, v89
	v_cvt_pk_bf16_f32 v155, v90, v91
	ds_read_b64_tr_b16 v[84:85], v207 offset:25600
	ds_read_b64_tr_b16 v[86:87], v207 offset:26112
	v_add_f32_e32 v2, v94, v2
	v_add_f32_e32 v2, v95, v2
	v_add_f32_e32 v2, v96, v2
	v_add_f32_e32 v2, v97, v2
	v_cvt_pk_bf16_f32 v148, v92, v93
	v_cvt_pk_bf16_f32 v149, v94, v95
	s_waitcnt lgkmcnt(4)
	v_mfma_f32_32x32x16_bf16 v[132:147], v[168:171], v[4:7], v[132:147]
	v_mfma_f32_32x32x16_bf16 v[116:131], v[164:167], v[4:7], v[116:131]
	v_add_f32_e32 v2, v98, v2
	v_add_f32_e32 v2, v99, v2
	v_add_f32_e32 v2, 0, v2
	v_cvt_pk_bf16_f32 v150, v96, v97
	v_cvt_pk_bf16_f32 v151, v98, v99
	v_lshl_add_u64 v[12:13], v[204:205], 0, s[6:7]
	v_lshl_add_u64 v[10:11], v[8:9], 0, s[6:7]
	v_add_f32_e32 v2, v225, v2
	ds_read_b64_tr_b16 v[4:5], v207 offset:29696
	ds_read_b64_tr_b16 v[6:7], v207 offset:30208
	v_mfma_f32_32x32x16_bf16 v[68:83], v[160:163], v[14:17], v[68:83]
	v_exp_f32_e32 v132, v132
	v_exp_f32_e32 v133, v133
	ds_read_b64_tr_b16 v[14:15], v207 offset:26624
	ds_read_b64_tr_b16 v[16:17], v207 offset:27136
	s_waitcnt lgkmcnt(6)
	v_mfma_f32_32x32x16_bf16 v[52:67], v[160:163], v[100:103], v[52:67]
	v_exp_f32_e32 v134, v134
	v_exp_f32_e32 v135, v135
	s_add_u32 s98, s6, s28
	s_addc_u32 s99, s7, s29
	v_lshl_add_u64 v[254:255], v[204:205], 0, s[98:99]
	s_lshl_b32 s100, s59, 13
	s_add_i32 s100, s100, s49
	s_mov_b32 m0, s100
	s_nop 0
	global_load_lds_dwordx4 v[254:255], off
	ds_read_b64_tr_b16 v[88:89], v207 offset:30720
	ds_read_b64_tr_b16 v[90:91], v207 offset:31232
	s_waitcnt lgkmcnt(6)
	v_mfma_f32_32x32x16_bf16 v[68:83], v[156:159], v[84:87], v[68:83]
	v_exp_f32_e32 v136, v136
	v_exp_f32_e32 v137, v137
	ds_read_b64_tr_b16 v[84:85], v207 offset:27648
	ds_read_b64_tr_b16 v[86:87], v207 offset:28160
	s_waitcnt lgkmcnt(6)
	v_mfma_f32_32x32x16_bf16 v[52:67], v[156:159], v[4:7], v[52:67]
	v_exp_f32_e32 v138, v138
	v_exp_f32_e32 v139, v139
	ds_read_b64_tr_b16 v[4:5], v207 offset:31744
	ds_read_b64_tr_b16 v[6:7], v207 offset:32256
	s_waitcnt lgkmcnt(6)
	v_mfma_f32_32x32x16_bf16 v[68:83], v[152:155], v[14:17], v[68:83]
	v_exp_f32_e32 v140, v140
	v_exp_f32_e32 v141, v141
	s_add_u32 s98, s6, s30
	s_addc_u32 s99, s7, s31
	v_lshl_add_u64 v[254:255], v[8:9], 0, s[98:99]
	s_lshl_b32 s100, s60, 14
	s_add_i32 s100, s100, s58
	s_mov_b32 m0, s100
	s_nop 0
	global_load_lds_dwordx4 v[254:255], off
	ds_read_b64_tr_b16 v[14:15], v207 offset:32768
	ds_read_b64_tr_b16 v[16:17], v207 offset:33280
	s_waitcnt lgkmcnt(6)
	v_mfma_f32_32x32x16_bf16 v[52:67], v[152:155], v[88:91], v[52:67]
	v_exp_f32_e32 v142, v142
	v_exp_f32_e32 v143, v143
	ds_read_b64_tr_b16 v[88:89], v207 offset:36864
	ds_read_b64_tr_b16 v[90:91], v207 offset:37376
	s_waitcnt lgkmcnt(6)
	v_mfma_f32_32x32x16_bf16 v[68:83], v[148:151], v[84:87], v[68:83]
	v_exp_f32_e32 v144, v144
	v_exp_f32_e32 v145, v145
	ds_read_b64_tr_b16 v[84:85], v207 offset:33792
	ds_read_b64_tr_b16 v[86:87], v207 offset:34304
	s_waitcnt lgkmcnt(6)
	v_mfma_f32_32x32x16_bf16 v[52:67], v[148:151], v[4:7], v[52:67]
	v_exp_f32_e32 v146, v146
	v_exp_f32_e32 v147, v147
	ds_read_b64_tr_b16 v[92:93], v207 offset:37888
	ds_read_b64_tr_b16 v[94:95], v207 offset:38400
	s_lshl_b32 s11, s60, 13
	v_add_u32_e32 v4, s11, v222
	ds_read_b128 v[96:99], v4
	ds_read_b128 v[164:167], v4 offset:512
	s_waitcnt lgkmcnt(8)
	v_mfma_f32_32x32x16_bf16 v[36:51], v[160:163], v[14:17], v[36:51]
	v_exp_f32_e32 v116, v116
	v_exp_f32_e32 v117, v117
	ds_read_b64_tr_b16 v[14:15], v207 offset:34816
	ds_read_b64_tr_b16 v[16:17], v207 offset:35328
	ds_read_b128 v[168:171], v4 offset:2048
	ds_read_b128 v[172:175], v4 offset:2560
	s_waitcnt lgkmcnt(10)
; #define TWAIT_BAR(N) asm volatile("s_waitcnt vmcnt(" #N ") lgkmcnt(0)\n\ts_barrier" ::: "memory")
; #define RESC() do { if constexpr (!NOMAX) if (resc) { asm volatile("s_waitcnt lgkmcnt(0)" ::: "memory"); \
;         _Pragma("unroll") for (int d_ = 0; d_ < 2; ++d_) _Pragma("unroll") for (int r = 0; r < 16; ++r) o[d_][r] *= wsf[crow(r, hi)]; } } while (0)
; #define ROT() do { sl_prev = sl_cur; sl_cur = sl_next; sl_next = (sl_next == 2 * SLOTB) ? 0 : sl_next + SLOTB; } while (0)
; #define RESC() do { if constexpr (!NOMAX) if (resc) { asm volatile("s_waitcnt lgkmcnt(0)" ::: "memory"); \
;         _Pragma("unroll") for (int d_ = 0; d_ < 4; ++d_) _Pragma("unroll") for (int r = 0; r < 16; ++r) o[d_][r] *= wsf[crow(r, hi)]; } } while (0)
; #define ROT() do { sl_prev = sl_cur; sl_cur = sl_next; sl_next = (sl_next == 2) ? 0 : sl_next + 1; } while (0)
; #define RESC() do { if (resc) { asm volatile("s_waitcnt lgkmcnt(0)" ::: "memory"); \
;         _Pragma("unroll") for (int d_ = 0; d_ < 4; ++d_) _Pragma("unroll") for (int r = 0; r < 16; ++r) o[d_][r] *= wsf[crow(r, hi)]; } } while (0)
; template <bool NOMAX>
; __device__ __forceinline__ void diff_unit(const AttnCtx& C, int u, LAS unsigned char* lds) {
;     ...
;     int kk = 1;
;     for (; kk + 7 < n; kk += 2) {
;         STEP(pB0, pB1, pA0, pA1, kk, true, true, true, false);     TWAIT_BAR(3); RESC(); ROT();
;         STEP(pA0, pA1, pB0, pB1, kk + 1, true, true, true, false); TWAIT_BAR(3); RESC(); ROT();
	v_mfma_f32_32x32x16_bf16 v[20:35], v[160:163], v[88:91], v[20:35]
	v_exp_f32_e32 v118, v118
	v_exp_f32_e32 v119, v119
	ds_read_b64_tr_b16 v[88:89], v207 offset:38912
	ds_read_b64_tr_b16 v[90:91], v207 offset:39424
	ds_read_b128 v[176:179], v4 offset:4096
	ds_read_b128 v[180:183], v4 offset:4608
	s_waitcnt lgkmcnt(12)
	v_mfma_f32_32x32x16_bf16 v[36:51], v[156:159], v[84:87], v[36:51]
	v_exp_f32_e32 v120, v120
	v_exp_f32_e32 v121, v121
	ds_read_b64_tr_b16 v[84:85], v207 offset:35840
	ds_read_b64_tr_b16 v[86:87], v207 offset:36352
	ds_read_b128 v[184:187], v4 offset:6144
	ds_read_b128 v[4:7], v4 offset:6656
	s_waitcnt lgkmcnt(14)
	v_mfma_f32_32x32x16_bf16 v[20:35], v[156:159], v[92:95], v[20:35]
	v_exp_f32_e32 v122, v122
	v_exp_f32_e32 v123, v123
	ds_read_b64_tr_b16 v[92:93], v207 offset:39936
	ds_read_b64_tr_b16 v[94:95], v207 offset:40448
	s_waitcnt lgkmcnt(12)
	v_mfma_f32_32x32x16_bf16 v[36:51], v[152:155], v[14:17], v[36:51]
	v_exp_f32_e32 v124, v124
	v_exp_f32_e32 v125, v125
	ds_read_b128 v[14:17], v219
	s_waitcnt lgkmcnt(9)
	v_mfma_f32_32x32x16_bf16 v[20:35], v[152:155], v[88:91], v[20:35]
	v_exp_f32_e32 v126, v126
	v_exp_f32_e32 v127, v127
	s_add_u32 s98, s6, s34
	s_addc_u32 s99, s7, s35
	v_lshl_add_u64 v[254:255], v[8:9], 0, s[98:99]
	s_lshl_b32 s100, s60, 14
	s_add_i32 s100, s100, s58
	s_addk_i32 s100, 0x2000
	s_mov_b32 m0, s100
	s_nop 0
	global_load_lds_dwordx4 v[254:255], off
	s_waitcnt lgkmcnt(5)
	v_mfma_f32_32x32x16_bf16 v[36:51], v[148:151], v[84:87], v[36:51]
	v_exp_f32_e32 v128, v128
	v_exp_f32_e32 v129, v129
	s_waitcnt lgkmcnt(1)
	v_mfma_f32_32x32x16_bf16 v[20:35], v[148:151], v[92:95], v[20:35]
	v_exp_f32_e32 v130, v130
	v_exp_f32_e32 v131, v131
	s_waitcnt vmcnt(3) lgkmcnt(0)
	s_barrier
	s_add_i32 s16, s60, 1
	s_cmp_lg_u32 s60, 2
	s_cselect_b32 s59, s16, 0
	ds_read_b128 v[188:191], v219 offset:1024
	v_lshl_add_u32 v207, s10, 14, v214
	s_waitcnt lgkmcnt(1)
	v_mfma_f32_32x32x16_bf16 v[100:115], v[96:99], v[14:17], 0
	v_add_f32_e32 v84, v132, v133
	v_add_f32_e32 v84, v134, v84
	v_add_f32_e32 v84, v135, v84
	v_add_f32_e32 v84, v136, v84
	v_add_f32_e32 v84, v137, v84
	v_cvt_pk_bf16_f32 v160, v132, v133
	v_cvt_pk_bf16_f32 v161, v134, v135
	s_nop 0
	v_add_f32_e32 v84, v138, v84
	v_add_f32_e32 v84, v139, v84
	v_add_f32_e32 v84, v140, v84
	v_add_f32_e32 v148, v141, v84
	v_mfma_f32_32x32x16_bf16 v[84:99], v[164:167], v[14:17], 0
	v_cvt_pk_bf16_f32 v162, v136, v137
	v_cvt_pk_bf16_f32 v163, v138, v139
	ds_read_b128 v[14:17], v219 offset:2048
	ds_read_b64_tr_b16 v[132:133], v207 offset:24576
	ds_read_b64_tr_b16 v[134:135], v207 offset:25088
	s_waitcnt lgkmcnt(3)
	v_mfma_f32_32x32x16_bf16 v[100:115], v[168:171], v[188:191], v[100:115]
	v_add_f32_e32 v136, v142, v148
	v_add_f32_e32 v136, v143, v136
	v_add_f32_e32 v136, v144, v136
	v_add_f32_e32 v136, v145, v136
	v_cvt_pk_bf16_f32 v156, v140, v141
	v_cvt_pk_bf16_f32 v157, v142, v143
	v_mfma_f32_32x32x16_bf16 v[84:99], v[172:175], v[188:191], v[84:99]
	v_add_f32_e32 v136, v146, v136
	v_add_f32_e32 v136, v147, v136
	v_add_f32_e32 v136, v116, v136
	v_add_f32_e32 v148, v117, v136
	v_cvt_pk_bf16_f32 v158, v144, v145
	v_cvt_pk_bf16_f32 v159, v146, v147
	ds_read_b128 v[136:139], v219 offset:3072
	ds_read_b64_tr_b16 v[140:141], v207 offset:28672
	ds_read_b64_tr_b16 v[142:143], v207 offset:29184
	s_waitcnt lgkmcnt(5)
	v_mfma_f32_32x32x16_bf16 v[100:115], v[176:179], v[14:17], v[100:115]
	v_add_f32_e32 v144, v118, v148
	v_add_f32_e32 v144, v119, v144
	v_add_f32_e32 v144, v120, v144
	v_add_f32_e32 v144, v121, v144
	v_cvt_pk_bf16_f32 v152, v116, v117
	v_cvt_pk_bf16_f32 v153, v118, v119
	v_mfma_f32_32x32x16_bf16 v[84:99], v[180:183], v[14:17], v[84:99]
	v_add_f32_e32 v14, v122, v144
	v_add_f32_e32 v14, v123, v14
	v_add_f32_e32 v14, v124, v14
	v_add_f32_e32 v116, v125, v14
	v_cvt_pk_bf16_f32 v154, v120, v121
	v_cvt_pk_bf16_f32 v155, v122, v123
	ds_read_b64_tr_b16 v[14:15], v207 offset:25600
	ds_read_b64_tr_b16 v[16:17], v207 offset:26112
	s_waitcnt lgkmcnt(4)
	v_mfma_f32_32x32x16_bf16 v[100:115], v[184:187], v[136:139], v[100:115]
	v_add_f32_e32 v116, v126, v116
	v_add_f32_e32 v116, v127, v116
	v_add_f32_e32 v116, v128, v116
	v_add_f32_e32 v116, v129, v116
	v_cvt_pk_bf16_f32 v148, v124, v125
	v_cvt_pk_bf16_f32 v149, v126, v127
	v_mfma_f32_32x32x16_bf16 v[84:99], v[4:7], v[136:139], v[84:99]
	v_add_f32_e32 v4, v130, v116
	v_add_f32_e32 v4, v131, v4
	v_add_f32_e32 v4, 0, v4
	v_cvt_pk_bf16_f32 v150, v128, v129
	v_cvt_pk_bf16_f32 v151, v130, v131
	v_add_f32_e32 v225, v2, v4
	ds_read_b64_tr_b16 v[4:5], v207 offset:29696
	ds_read_b64_tr_b16 v[6:7], v207 offset:30208
	v_mfma_f32_32x32x16_bf16 v[68:83], v[160:163], v[132:135], v[68:83]
	v_exp_f32_e32 v100, v100
	v_exp_f32_e32 v101, v101
	ds_read_b64_tr_b16 v[10:11], v207 offset:26624
	ds_read_b64_tr_b16 v[12:13], v207 offset:27136
	s_waitcnt lgkmcnt(6)
; #define TWAIT_BAR(N) asm volatile("s_waitcnt vmcnt(" #N ") lgkmcnt(0)\n\ts_barrier" ::: "memory")
; #define RESC() do { if constexpr (!NOMAX) if (resc) { asm volatile("s_waitcnt lgkmcnt(0)" ::: "memory"); \
;         _Pragma("unroll") for (int d_ = 0; d_ < 2; ++d_) _Pragma("unroll") for (int r = 0; r < 16; ++r) o[d_][r] *= wsf[crow(r, hi)]; } } while (0)
; #define ROT() do { sl_prev = sl_cur; sl_cur = sl_next; sl_next = (sl_next == 2 * SLOTB) ? 0 : sl_next + SLOTB; } while (0)
; #define RESC() do { if constexpr (!NOMAX) if (resc) { asm volatile("s_waitcnt lgkmcnt(0)" ::: "memory"); \
;         _Pragma("unroll") for (int d_ = 0; d_ < 4; ++d_) _Pragma("unroll") for (int r = 0; r < 16; ++r) o[d_][r] *= wsf[crow(r, hi)]; } } while (0)
; #define ROT() do { sl_prev = sl_cur; sl_cur = sl_next; sl_next = (sl_next == 2) ? 0 : sl_next + 1; } while (0)
; #define RESC() do { if (resc) { asm volatile("s_waitcnt lgkmcnt(0)" ::: "memory"); \
;         _Pragma("unroll") for (int d_ = 0; d_ < 4; ++d_) _Pragma("unroll") for (int r = 0; r < 16; ++r) o[d_][r] *= wsf[crow(r, hi)]; } } while (0)
; template <bool NOMAX>
; __device__ __forceinline__ void diff_unit(const AttnCtx& C, int u, LAS unsigned char* lds) {
;     ...
;     int kk = 1;
;     for (; kk + 7 < n; kk += 2) {
;         STEP(pB0, pB1, pA0, pA1, kk, true, true, true, false);     TWAIT_BAR(3); RESC(); ROT();
;         STEP(pA0, pA1, pB0, pB1, kk + 1, true, true, true, false); TWAIT_BAR(3); RESC(); ROT();
	v_mfma_f32_32x32x16_bf16 v[52:67], v[160:163], v[140:143], v[52:67]
	v_exp_f32_e32 v102, v102
	v_exp_f32_e32 v103, v103
	s_add_u32 s98, s6, s36
	s_addc_u32 s99, s7, s37
	v_lshl_add_u64 v[254:255], v[204:205], 0, s[98:99]
	s_lshl_b32 s100, s60, 13
	s_add_i32 s100, s100, s49
	s_mov_b32 m0, s100
	s_nop 0
	global_load_lds_dwordx4 v[254:255], off
	ds_read_b64_tr_b16 v[116:117], v207 offset:30720
	ds_read_b64_tr_b16 v[118:119], v207 offset:31232
	s_waitcnt lgkmcnt(6)
	v_mfma_f32_32x32x16_bf16 v[68:83], v[156:159], v[14:17], v[68:83]
	v_exp_f32_e32 v104, v104
	v_exp_f32_e32 v105, v105
	ds_read_b64_tr_b16 v[14:15], v207 offset:27648
	ds_read_b64_tr_b16 v[16:17], v207 offset:28160
	s_waitcnt lgkmcnt(6)
	v_mfma_f32_32x32x16_bf16 v[52:67], v[156:159], v[4:7], v[52:67]
	v_exp_f32_e32 v106, v106
	v_exp_f32_e32 v107, v107
	ds_read_b64_tr_b16 v[4:5], v207 offset:31744
	ds_read_b64_tr_b16 v[6:7], v207 offset:32256
	s_waitcnt lgkmcnt(6)
	v_mfma_f32_32x32x16_bf16 v[68:83], v[152:155], v[10:13], v[68:83]
	v_exp_f32_e32 v108, v108
	v_exp_f32_e32 v109, v109
	s_add_u32 s98, s6, s38
	s_addc_u32 s99, s7, s39
	v_lshl_add_u64 v[254:255], v[8:9], 0, s[98:99]
	s_lshl_b32 s100, s59, 14
	s_add_i32 s100, s100, s58
	s_mov_b32 m0, s100
	s_nop 0
	global_load_lds_dwordx4 v[254:255], off
	ds_read_b64_tr_b16 v[10:11], v207 offset:32768
	ds_read_b64_tr_b16 v[12:13], v207 offset:33280
	s_waitcnt lgkmcnt(6)
	v_mfma_f32_32x32x16_bf16 v[52:67], v[152:155], v[116:119], v[52:67]
	v_exp_f32_e32 v110, v110
	v_exp_f32_e32 v111, v111
	ds_read_b64_tr_b16 v[116:117], v207 offset:36864
	ds_read_b64_tr_b16 v[118:119], v207 offset:37376
	s_waitcnt lgkmcnt(6)
	v_mfma_f32_32x32x16_bf16 v[68:83], v[148:151], v[14:17], v[68:83]
	v_exp_f32_e32 v112, v112
	v_exp_f32_e32 v113, v113
	ds_read_b64_tr_b16 v[14:15], v207 offset:33792
	ds_read_b64_tr_b16 v[16:17], v207 offset:34304
	s_waitcnt lgkmcnt(6)
	v_mfma_f32_32x32x16_bf16 v[52:67], v[148:151], v[4:7], v[52:67]
	v_exp_f32_e32 v114, v114
	v_exp_f32_e32 v115, v115
	ds_read_b64_tr_b16 v[4:5], v207 offset:37888
	ds_read_b64_tr_b16 v[6:7], v207 offset:38400
	v_lshl_add_u32 v2, s59, 13, v222
	ds_read_b128 v[192:195], v2
	ds_read_b128 v[184:187], v2 offset:512
	s_waitcnt lgkmcnt(8)
	v_mfma_f32_32x32x16_bf16 v[36:51], v[160:163], v[10:13], v[36:51]
	v_exp_f32_e32 v84, v84
	v_exp_f32_e32 v85, v85
	ds_read_b64_tr_b16 v[10:11], v207 offset:34816
	ds_read_b64_tr_b16 v[12:13], v207 offset:35328
	ds_read_b128 v[188:191], v2 offset:2048
	ds_read_b128 v[180:183], v2 offset:2560
	s_waitcnt lgkmcnt(10)
	v_mfma_f32_32x32x16_bf16 v[20:35], v[160:163], v[116:119], v[20:35]
	v_exp_f32_e32 v86, v86
	v_exp_f32_e32 v87, v87
	ds_read_b64_tr_b16 v[120:121], v207 offset:38912
	ds_read_b64_tr_b16 v[122:123], v207 offset:39424
	ds_read_b128 v[176:179], v2 offset:4096
	ds_read_b128 v[172:175], v2 offset:4608
	s_waitcnt lgkmcnt(12)
	v_mfma_f32_32x32x16_bf16 v[36:51], v[156:159], v[14:17], v[36:51]
	v_exp_f32_e32 v88, v88
	v_exp_f32_e32 v89, v89
	ds_read_b64_tr_b16 v[14:15], v207 offset:35840
	ds_read_b64_tr_b16 v[16:17], v207 offset:36352
	ds_read_b128 v[168:171], v2 offset:6144
	ds_read_b128 v[164:167], v2 offset:6656
	s_waitcnt lgkmcnt(14)
	v_mfma_f32_32x32x16_bf16 v[20:35], v[156:159], v[4:7], v[20:35]
	v_exp_f32_e32 v90, v90
	v_exp_f32_e32 v91, v91
	ds_read_b64_tr_b16 v[4:5], v207 offset:39936
	ds_read_b64_tr_b16 v[6:7], v207 offset:40448
	s_waitcnt lgkmcnt(12)
	v_mfma_f32_32x32x16_bf16 v[36:51], v[152:155], v[10:13], v[36:51]
	v_exp_f32_e32 v92, v92
	v_exp_f32_e32 v93, v93
	ds_read_b128 v[116:119], v219
	s_waitcnt lgkmcnt(9)
	v_mfma_f32_32x32x16_bf16 v[20:35], v[152:155], v[120:123], v[20:35]
	v_exp_f32_e32 v94, v94
	v_exp_f32_e32 v95, v95
	s_add_u32 s98, s6, s40
	s_addc_u32 s99, s7, s41
	v_lshl_add_u64 v[254:255], v[8:9], 0, s[98:99]
	s_lshl_b32 s100, s59, 14
	s_add_i32 s100, s100, s58
	s_addk_i32 s100, 0x2000
	s_mov_b32 m0, s100
	s_nop 0
	global_load_lds_dwordx4 v[254:255], off
	s_waitcnt lgkmcnt(5)
	v_mfma_f32_32x32x16_bf16 v[36:51], v[148:151], v[14:17], v[36:51]
	v_exp_f32_e32 v96, v96
	v_exp_f32_e32 v97, v97
	s_waitcnt lgkmcnt(1)
	v_mfma_f32_32x32x16_bf16 v[20:35], v[148:151], v[4:7], v[20:35]
	v_exp_f32_e32 v98, v98
	v_exp_f32_e32 v99, v99
	s_add_i32 s10, s59, 1
	s_cmp_lg_u32 s59, 2
	s_waitcnt vmcnt(3) lgkmcnt(0)
	s_barrier
	s_cselect_b32 s60, s10, 0
	s_add_i32 s16, s9, 2
	s_add_u32 s6, s6, 0x20000
	v_cmp_ge_u32_e32 vcc, s16, v226
	s_addc_u32 s7, s7, 0
	s_mov_b32 s11, s8
	s_cbranch_vccz .LBB0_463
	s_add_i32 s16, s9, -5
	s_branch .LBB0_467
